# same as previous best plus a 2-state pad between the VALU address add and v_readfirstlane in the Q-staging prologue (hazard row: VALU write -> readfirstlane)
# baseline (speedup 1.0000x reference)
; #define AT_LOAD(st) do { _Pragma("unroll") for (int e = 0; e < 3; ++e) pk[e] = *(const u32x4*)(kbase + (size_t)((st) * 64 + krow[e]) * 768 + kcol[e] * 8); \
;         _Pragma("unroll") for (int e = 0; e < 2; ++e) { const int c = tid + 512 * e; pv[e] = *(const u32x4*)(vbase + (size_t)(c >> 3) * SEQ + (st) * 64 + (c & 7) * 8); } } while (0)
; DI void attn_unit(const Params& p, int b, int h, int qb, LAS unsigned char* lds, int tid, int lane, int wave) {
;     ...
;     const int g = wave >> 2, w4 = wave & 3, r = lane & 31, hh = lane >> 5;
;     const int qr0 = qb * 128 + w4 * 32, nst = 2 * (qb + 1);
;     const size_t tokb = (size_t)b * SEQ;
;     bf16x8 qf[12];
;     { const bf16_t* qp = Q + (tokb + qr0 + r) * 768 + h * 192 + 8 * hh;
; #pragma unroll
;       for (int kk = 0; kk < 12; ++kk) qf[kk] = *(const bf16x8*)(qp + 16 * kk); }
;     f32x16 o[4];
; #pragma unroll
;     for (int i = 0; i < 4; ++i)
; #pragma unroll
;         for (int j = 0; j < 16; ++j) o[i][j] = 0.f;
;     float mrow = -INFINITY, lrow = 0.f;
;     const bf16_t* kbase = KB + tokb * 768 + h * 192;
;     const bf16_t* vbase = VT + (size_t)((b * 4 + h) * 128) * SEQ;
;     int krow[3], kcol[3];
; #pragma unroll
;     for (int e = 0; e < 3; ++e) { const int c = tid + 512 * e; krow[e] = c / 24; kcol[e] = c % 24; }
;     u32x4 pk[3], pv[2];
;     ...
;     AT_LOAD(0); AT_WRITE(0);
.LBB0_426:
	s_mov_b32 s3, s33
	v_mbcnt_lo_u32_b32 v183, -1, 0
	v_mbcnt_hi_u32_b32 v183, -1, v183
	s_mov_b32 s5, 0x2aaaaaab
	v_lshl_add_u32 v14, s3, 6, v183
	v_mul_hi_i32 v0, v14, s5
	v_lshrrev_b32_e32 v2, 31, v0
	v_ashrrev_i32_e32 v0, 2, v0
	v_add_u32_e32 v40, v0, v2
	s_bfe_u32 s4, s73, 0x20006
	s_bfe_u32 s2, s73, 0x20004
	v_mul_lo_u32 v0, v40, 24
	s_waitcnt vmcnt(0)
	v_add_u32_e32 v20, 0x200, v14
	s_lshl_b32 s0, s2, 20
	s_lshl_b32 s1, s4, 22
	v_sub_u32_e32 v41, v14, v0
	v_mul_hi_i32 v0, v20, s5
	s_or_b32 s92, s1, s0
	s_mov_b64 s[0:1], s[50:51]
	v_lshrrev_b32_e32 v2, 31, v0
	v_ashrrev_i32_e32 v0, 2, v0
	s_and_b32 s94, s73, 15
	v_add_u32_e32 v42, v0, v2
	s_xor_b32 s0, s94, 31
	s_and_b32 s20, s3, 3
	v_mul_lo_u32 v0, v42, 24
	s_lshl_b32 s6, s0, 7
	s_lshl_b32 s0, s20, 5
	s_mul_i32 s67, s2, 0xc0
	v_sub_u32_e32 v43, v20, v0
	v_add_u32_e32 v0, 0x400, v14
	s_or_b32 s36, s0, s6
	s_lshl_b32 s66, s4, 12
	s_lshl_b32 s0, s67, 1
	s_ashr_i32 s21, s3, 2
	s_mul_i32 s7, s4, 0x600000
	v_readlane_b32 s1, v254, 52
	v_mul_hi_i32 v2, v0, s5
	s_add_u32 s1, s1, s7
	v_readlane_b32 s4, v254, 53
	v_lshrrev_b32_e32 v3, 31, v2
	v_ashrrev_i32_e32 v2, 2, v2
	s_addc_u32 s4, s4, 0
	v_add_u32_e32 v44, v2, v3
	v_mul_lo_u32 v2, v44, 24
	s_add_u32 s52, s1, s0
	v_sub_u32_e32 v45, v0, v2
	s_addc_u32 s53, s4, 0
	v_lshlrev_b32_e32 v4, 3, v41
	v_lshlrev_b32_e32 v6, 3, v43
	v_mov_b64_e32 v[10:11], s[52:53]
	v_ashrrev_i32_e32 v5, 31, v4
	v_ashrrev_i32_e32 v7, 31, v6
	v_lshlrev_b32_e32 v12, 3, v45
	v_readlane_b32 s1, v254, 50
	v_mad_i64_i32 v[2:3], s[4:5], v40, s76, v[10:11]
	v_lshlrev_b64 v[22:23], 1, v[4:5]
	v_mad_i64_i32 v[4:5], s[4:5], v42, s76, v[10:11]
	v_lshlrev_b64 v[24:25], 1, v[6:7]
	v_ashrrev_i32_e32 v13, 31, v12
	s_add_u32 s74, s1, s92
	v_readlane_b32 s1, v254, 51
	v_lshlrev_b32_e32 v0, 4, v183
	v_ashrrev_i32_e32 v28, 3, v14
	v_lshl_add_u64 v[2:3], v[2:3], 0, v[22:23]
	v_lshl_add_u64 v[6:7], v[4:5], 0, v[24:25]
	v_mad_i64_i32 v[10:11], s[4:5], v44, s76, v[10:11]
	v_lshlrev_b64 v[26:27], 1, v[12:13]
	s_addc_u32 s75, s1, 0
	v_and_b32_e32 v0, 0x70, v0
	v_ashrrev_i32_e32 v29, 31, v28
	v_ashrrev_i32_e32 v32, 3, v20
	global_load_dwordx4 v[2:5], v[2:3], off
	s_nop 0
	global_load_dwordx4 v[6:9], v[6:7], off
	v_lshl_add_u64 v[10:11], v[10:11], 0, v[26:27]
	v_lshl_add_u64 v[18:19], s[74:75], 0, v[0:1]
	v_lshlrev_b64 v[30:31], 13, v[28:29]
	v_ashrrev_i32_e32 v33, 31, v32
	global_load_dwordx4 v[10:13], v[10:11], off
	v_lshl_add_u64 v[14:15], v[18:19], 0, v[30:31]
	v_lshlrev_b64 v[34:35], 13, v[32:33]
	v_and_b32_e32 v29, 31, v183
	v_readlane_b32 s4, v254, 48
	global_load_dwordx4 v[14:17], v[14:15], off
	v_lshl_add_u64 v[18:19], v[18:19], 0, v[34:35]
	v_or_b32_e32 v36, s66, v29
	v_readlane_b32 s5, v254, 49
	global_load_dwordx4 v[18:21], v[18:19], off
	v_ashrrev_i32_e32 v33, 5, v183
	v_or_b32_e32 v202, s36, v36
	v_mov_b64_e32 v[36:37], s[4:5]
	v_mad_u64_u32 v[36:37], s[4:5], v202, s76, v[36:37]
	s_mov_b32 s1, s93
	v_lshlrev_b32_e32 v38, 3, v33
	v_lshl_add_u64 v[36:37], v[36:37], 0, s[0:1]
	v_ashrrev_i32_e32 v39, 31, v38
	v_lshl_add_u64 v[36:37], v[38:39], 1, v[36:37]
	s_nop 0
	s_nop 0
	v_readfirstlane_b32 s0, v36
	v_readfirstlane_b32 s1, v37
	s_lshr_b32 vcc_hi, s3, 2
	s_mul_i32 vcc_lo, s20, 0x3200
	s_add_u32 vcc_lo, vcc_lo, 0x15800
	s_mulk_i32 vcc_hi, 0x180
	v_add_u32_e32 v78, vcc_hi, v183
	v_mul_u32_u24_e32 v79, 0xaaab, v78
	v_lshrrev_b32_e32 v79, 20, v79
	v_mul_u32_u24_e32 v80, 24, v79
	v_sub_u32_e32 v80, v78, v80
	v_lshlrev_b32_e32 v80, 4, v80
	v_mad_u32_u24 v81, v79, s76, v80
	v_mad_u32_u24 v66, v79, s77, v80
	v_add_u32_e32 v66, vcc_lo, v66
	global_load_dwordx4 v[130:133], v81, s[0:1]
	v_add_u32_e32 v78, 64, v78
	v_mul_u32_u24_e32 v79, 0xaaab, v78
	v_lshrrev_b32_e32 v79, 20, v79
	v_mul_u32_u24_e32 v80, 24, v79
	v_sub_u32_e32 v80, v78, v80
	v_lshlrev_b32_e32 v80, 4, v80
	v_mad_u32_u24 v81, v79, s76, v80
	v_mad_u32_u24 v67, v79, s77, v80
	v_add_u32_e32 v67, vcc_lo, v67
	global_load_dwordx4 v[134:137], v81, s[0:1]
	v_add_u32_e32 v78, 64, v78
	v_mul_u32_u24_e32 v79, 0xaaab, v78
	v_lshrrev_b32_e32 v79, 20, v79
	v_mul_u32_u24_e32 v80, 24, v79
	v_sub_u32_e32 v80, v78, v80
	v_lshlrev_b32_e32 v80, 4, v80
	v_mad_u32_u24 v81, v79, s76, v80
	v_mad_u32_u24 v68, v79, s77, v80
	v_add_u32_e32 v68, vcc_lo, v68
	global_load_dwordx4 v[138:141], v81, s[0:1]
	v_add_u32_e32 v78, 64, v78
	v_mul_u32_u24_e32 v79, 0xaaab, v78
	v_lshrrev_b32_e32 v79, 20, v79
	v_mul_u32_u24_e32 v80, 24, v79
	v_sub_u32_e32 v80, v78, v80
	v_lshlrev_b32_e32 v80, 4, v80
	v_mad_u32_u24 v81, v79, s76, v80
	v_mad_u32_u24 v69, v79, s77, v80
	v_add_u32_e32 v69, vcc_lo, v69
	global_load_dwordx4 v[142:145], v81, s[0:1]
	v_add_u32_e32 v78, 64, v78
	v_mul_u32_u24_e32 v79, 0xaaab, v78
	v_lshrrev_b32_e32 v79, 20, v79
	v_mul_u32_u24_e32 v80, 24, v79
	v_sub_u32_e32 v80, v78, v80
	v_lshlrev_b32_e32 v80, 4, v80
	v_mad_u32_u24 v81, v79, s76, v80
	v_mad_u32_u24 v70, v79, s77, v80
	v_add_u32_e32 v70, vcc_lo, v70
	global_load_dwordx4 v[146:149], v81, s[0:1]
	v_add_u32_e32 v78, 64, v78
	v_mul_u32_u24_e32 v79, 0xaaab, v78
	v_lshrrev_b32_e32 v79, 20, v79
	v_mul_u32_u24_e32 v80, 24, v79
	v_sub_u32_e32 v80, v78, v80
	v_lshlrev_b32_e32 v80, 4, v80
	v_mad_u32_u24 v81, v79, s76, v80
	v_mad_u32_u24 v71, v79, s77, v80
	v_add_u32_e32 v71, vcc_lo, v71
	global_load_dwordx4 v[150:153], v81, s[0:1]
	v_mul_lo_u32 v207, v40, s77
	v_lshlrev_b32_e32 v208, 4, v41
	v_add3_u32 v36, 0, v207, v208
	v_mul_lo_u32 v209, v42, s77
	v_lshlrev_b32_e32 v210, 4, v43
	v_mul_lo_u32 v211, v44, s77
	v_lshlrev_b32_e32 v212, 4, v45
	s_movk_i32 s0, 0x90
	v_bfe_u32 v222, v0, 4, 1
	v_and_b32_e32 v213, 0x60, v0
	v_lshl_or_b32 v213, v222, 3, v213
	v_mul_lo_u32 v214, v28, s0
	v_mul_lo_u32 v215, v32, s0
	s_lshl_b32 s56, s21, 5
	v_lshlrev_b32_e32 v182, 2, v33
	v_or_b32_e32 v205, s36, v29
	s_or_b32 s57, s36, 31
	s_or_b32 s59, s6, 64
	v_or_b32_e32 v30, v30, v0
	s_mov_b64 s[0:1], 0xe600080
	v_or_b32_e32 v34, v34, v0
	s_add_u32 s54, s7, 0xce18000
	s_addc_u32 s55, 0, 0
	v_mov_b32_e32 v0, 0x180
	s_mov_b32 s62, 0
	v_mov_b32_e32 v203, 0
	v_mov_b32_e32 v204, 0xff800000
	s_mov_b32 s63, 0
	s_waitcnt vmcnt(10)
; #define AT_LOAD(st) do { _Pragma("unroll") for (int e = 0; e < 3; ++e) pk[e] = *(const u32x4*)(kbase + (size_t)((st) * 64 + krow[e]) * 768 + kcol[e] * 8); \
;         _Pragma("unroll") for (int e = 0; e < 2; ++e) { const int c = tid + 512 * e; pv[e] = *(const u32x4*)(vbase + (size_t)(c >> 3) * SEQ + (st) * 64 + (c & 7) * 8); } } while (0)
; DI void attn_unit(const Params& p, int b, int h, int qb, LAS unsigned char* lds, int tid, int lane, int wave) {
;     ...
;     bf16x8 qf[12];
;     { const bf16_t* qp = Q + (tokb + qr0 + r) * 768 + h * 192 + 8 * hh;
; #pragma unroll
;       for (int kk = 0; kk < 12; ++kk) qf[kk] = *(const bf16x8*)(qp + 16 * kk); }
;     f32x16 o[4];
; #pragma unroll
;     for (int i = 0; i < 4; ++i)
; #pragma unroll
;         for (int j = 0; j < 16; ++j) o[i][j] = 0.f;
;     float mrow = -INFINITY, lrow = 0.f;
;     const bf16_t* kbase = KB + tokb * 768 + h * 192;
;     const bf16_t* vbase = VT + (size_t)((b * 4 + h) * 128) * SEQ;
;     int krow[3], kcol[3];
; #pragma unroll
;     for (int e = 0; e < 3; ++e) { const int c = tid + 512 * e; krow[e] = c / 24; kcol[e] = c % 24; }
;     u32x4 pk[3], pv[2];
;     ...
;     AT_LOAD(0); AT_WRITE(0);
;     __syncthreads();
	ds_write_b128 v36, v[2:5]
	v_add3_u32 v2, 0, v209, v210
	s_waitcnt vmcnt(9)
	ds_write_b128 v2, v[6:9]
	v_add3_u32 v2, 0, v211, v212
	v_lshlrev_b32_e32 v3, 4, v33
	v_mov_b32_e32 v6, v1
	s_waitcnt vmcnt(8)
	ds_write_b128 v2, v[10:13]
	v_add3_u32 v2, v213, v214, s65
	v_mov_b32_e32 v7, v1
	v_mov_b32_e32 v8, v1
	v_mov_b32_e32 v9, v1
	s_waitcnt vmcnt(7)
	ds_write2_b64 v2, v[14:15], v[16:17] offset1:2
	v_add3_u32 v2, v213, v215, s65
	v_mov_b32_e32 v14, v1
	v_mov_b32_e32 v15, v1
	s_waitcnt vmcnt(6)
	ds_write2_b64 v2, v[18:19], v[20:21] offset1:2
	v_or_b32_e32 v2, s56, v29
	v_mul_lo_u32 v2, v2, s77
	v_add3_u32 v216, 0, v2, v3
	v_mul_u32_u24_e32 v2, 0x90, v29
	v_lshlrev_b32_e32 v3, 2, v182
	v_lshl_add_u32 v3, s56, 1, v3
	v_add3_u32 v206, 0, v2, v3
	v_sub_u32_e32 v2, v205, v182
	v_subrev_u32_e32 v217, s56, v2
	v_lshl_add_u64 v[2:3], v[30:31], 0, s[92:93]
	v_lshl_add_u64 v[184:185], v[2:3], 0, s[0:1]
	v_lshl_add_u64 v[2:3], v[34:35], 0, s[92:93]
	v_lshl_add_u64 v[186:187], v[2:3], 0, s[0:1]
	v_mov_b64_e32 v[2:3], s[54:55]
	v_mad_i64_i32 v[4:5], s[0:1], v44, s76, v[2:3]
	v_mad_u64_u32 v[4:5], s[0:1], s2, v0, v[4:5]
	v_lshl_add_u64 v[188:189], v[4:5], 0, v[26:27]
	v_mad_i64_i32 v[4:5], s[0:1], v42, s76, v[2:3]
	v_mad_i64_i32 v[2:3], s[0:1], v40, s76, v[2:3]
	v_mad_u64_u32 v[4:5], s[0:1], s2, v0, v[4:5]
	v_mad_u64_u32 v[2:3], s[0:1], s2, v0, v[2:3]
	v_lshl_add_u64 v[190:191], v[4:5], 0, v[24:25]
	v_lshl_add_u64 v[192:193], v[2:3], 0, v[22:23]
	v_mov_b32_e32 v0, v1
	v_mov_b32_e32 v2, v1
	v_mov_b32_e32 v3, v1
	v_mov_b32_e32 v4, v1
	v_mov_b32_e32 v5, v1
	v_mov_b32_e32 v10, v1
	v_mov_b32_e32 v11, v1
	v_mov_b32_e32 v12, v1
	v_mov_b32_e32 v13, v1
	v_mov_b64_e32 v[64:65], v[14:15]
	v_mov_b64_e32 v[48:49], v[14:15]
	v_mov_b64_e32 v[32:33], v[14:15]
	v_mov_b64_e32 v[62:63], v[12:13]
	v_mov_b64_e32 v[60:61], v[10:11]
	v_mov_b64_e32 v[58:59], v[8:9]
	v_mov_b64_e32 v[56:57], v[6:7]
	v_mov_b64_e32 v[54:55], v[4:5]
	v_mov_b64_e32 v[52:53], v[2:3]
	v_mov_b64_e32 v[50:51], v[0:1]
	v_mov_b64_e32 v[46:47], v[12:13]
	v_mov_b64_e32 v[44:45], v[10:11]
	v_mov_b64_e32 v[42:43], v[8:9]
	v_mov_b64_e32 v[40:41], v[6:7]
	v_mov_b64_e32 v[38:39], v[4:5]
	v_mov_b64_e32 v[36:37], v[2:3]
	v_mov_b64_e32 v[34:35], v[0:1]
	v_mov_b64_e32 v[30:31], v[12:13]
	v_mov_b64_e32 v[28:29], v[10:11]
	v_mov_b64_e32 v[26:27], v[8:9]
	v_mov_b64_e32 v[24:25], v[6:7]
	v_mov_b64_e32 v[22:23], v[4:5]
	v_mov_b64_e32 v[20:21], v[2:3]
	v_mov_b64_e32 v[18:19], v[0:1]
	v_mov_b64_e32 v[16:17], v[14:15]
	v_mov_b64_e32 v[14:15], v[12:13]
	v_mov_b64_e32 v[12:13], v[10:11]
	v_mov_b64_e32 v[10:11], v[8:9]
	v_mov_b64_e32 v[8:9], v[6:7]
	v_mov_b64_e32 v[6:7], v[4:5]
	v_mov_b64_e32 v[4:5], v[2:3]
	v_mov_b64_e32 v[2:3], v[0:1]
	s_waitcnt vmcnt(5)
	ds_write_b128 v66, v[130:133]
	s_waitcnt vmcnt(4)
	ds_write_b128 v67, v[134:137]
	s_waitcnt vmcnt(3)
	ds_write_b128 v68, v[138:141]
	s_waitcnt vmcnt(2)
	ds_write_b128 v69, v[142:145]
	s_waitcnt vmcnt(1)
	ds_write_b128 v70, v[146:149]
	s_waitcnt vmcnt(0)
	ds_write_b128 v71, v[150:153]
	s_waitcnt lgkmcnt(0)
	s_barrier
	v_lshrrev_b32_e32 v78, 5, v183
	v_and_b32_e32 v79, 31, v183
	v_mul_u32_u24_e32 v79, s77, v79
	v_lshl_add_u32 v79, v78, 4, v79
	s_mul_i32 vcc_lo, s20, 0x3200
	s_add_u32 vcc_lo, vcc_lo, 0x15800
	v_add_u32_e32 v79, vcc_lo, v79
	ds_read_b128 v[126:129], v79
	ds_read_b128 v[122:125], v79 offset:32
	ds_read_b128 v[118:121], v79 offset:64
	ds_read_b128 v[114:117], v79 offset:96
	ds_read_b128 v[110:113], v79 offset:128
	ds_read_b128 v[106:109], v79 offset:160
	ds_read_b128 v[102:105], v79 offset:192
	ds_read_b128 v[98:101], v79 offset:224
	ds_read_b128 v[94:97], v79 offset:256
	ds_read_b128 v[90:93], v79 offset:288
	ds_read_b128 v[86:89], v79 offset:320
	ds_read_b128 v[82:85], v79 offset:352
	s_waitcnt vmcnt(0)
	v_mov_b64_e32 v[230:231], 0
	v_mov_b64_e32 v[232:233], 0
	v_mov_b64_e32 v[234:235], 0
	v_mov_b64_e32 v[236:237], 0
	v_mov_b64_e32 v[238:239], 0
	v_mov_b64_e32 v[240:241], 0
	v_mov_b64_e32 v[242:243], 0
	v_mov_b64_e32 v[244:245], 0
	v_mov_b32_e32 v246, 0xff800000
	v_lshl_add_u32 v222, s3, 6, v183
	v_and_b32_e32 v222, 0xff, v222
	s_movk_i32 s0, 0x600
	s_movk_i32 s1, 0x190
	s_cmp_lg_u32 s21, 0
	s_cbranch_scc1 .Lal1_b
	v_mov_b32_e32 v223, v222
	v_mul_u32_u24_e32 v224, 0xaaab, v223
	v_lshrrev_b32_e32 v224, 20, v224
	v_mul_u32_u24_e32 v225, 24, v224
	v_sub_u32_e32 v225, v223, v225
	v_lshlrev_b32_e32 v225, 4, v225
	v_mad_u32_u24 v184, v224, s0, v225
	v_mad_u32_u24 v190, v224, s1, v225
	v_add_u32_e32 v223, 256, v222
	v_mul_u32_u24_e32 v224, 0xaaab, v223
	v_lshrrev_b32_e32 v224, 20, v224
	v_mul_u32_u24_e32 v225, 24, v224
	v_sub_u32_e32 v225, v223, v225
	v_lshlrev_b32_e32 v225, 4, v225
	v_mad_u32_u24 v185, v224, s0, v225
	v_mad_u32_u24 v191, v224, s1, v225
	v_add_u32_e32 v223, 512, v222
	v_mul_u32_u24_e32 v224, 0xaaab, v223
	v_lshrrev_b32_e32 v224, 20, v224
	v_mul_u32_u24_e32 v225, 24, v224
	v_sub_u32_e32 v225, v223, v225
	v_lshlrev_b32_e32 v225, 4, v225
	v_mad_u32_u24 v186, v224, s0, v225
	v_mad_u32_u24 v192, v224, s1, v225
	v_add_u32_e32 v223, 768, v222
	v_mul_u32_u24_e32 v224, 0xaaab, v223
	v_lshrrev_b32_e32 v224, 20, v224
	v_mul_u32_u24_e32 v225, 24, v224
	v_sub_u32_e32 v225, v223, v225
	v_lshlrev_b32_e32 v225, 4, v225
	v_mad_u32_u24 v187, v224, s0, v225
	v_mad_u32_u24 v193, v224, s1, v225
	v_add_u32_e32 v223, 1024, v222
	v_mul_u32_u24_e32 v224, 0xaaab, v223
	v_lshrrev_b32_e32 v224, 20, v224
	v_mul_u32_u24_e32 v225, 24, v224
	v_sub_u32_e32 v225, v223, v225
	v_lshlrev_b32_e32 v225, 4, v225
	v_mad_u32_u24 v188, v224, s0, v225
	v_mad_u32_u24 v207, v224, s1, v225
	v_add_u32_e32 v223, 1280, v222
	v_mul_u32_u24_e32 v224, 0xaaab, v223
	v_lshrrev_b32_e32 v224, 20, v224
	v_mul_u32_u24_e32 v225, 24, v224
	v_sub_u32_e32 v225, v223, v225
	v_lshlrev_b32_e32 v225, 4, v225
	v_mad_u32_u24 v189, v224, s0, v225
	v_mad_u32_u24 v208, v224, s1, v225
	s_branch .Lal1_done

; #define LAS __attribute__((address_space(3)))
; #define AT_LOAD(st) do { _Pragma("unroll") for (int e = 0; e < 3; ++e) pk[e] = *(const u32x4*)(kbase + (size_t)((st) * 64 + krow[e]) * 768 + kcol[e] * 8); \
;         _Pragma("unroll") for (int e = 0; e < 2; ++e) { const int c = tid + 512 * e; pv[e] = *(const u32x4*)(vbase + (size_t)(c >> 3) * SEQ + (st) * 64 + (c & 7) * 8); } } while (0)
; DI void attn_unit(const Params& p, int b, int h, int qb, LAS unsigned char* lds, int tid, int lane, int wave) {
;     unsigned char* ws = p.ws;
;     const bf16_t* Q = (const bf16_t*)(ws + WS_QR); const bf16_t* KB = (const bf16_t*)(ws + WS_K); const bf16_t* VT = (const bf16_t*)(ws + WS_VT);
;     const bf16_t* Z = (const bf16_t*)(ws + WS_Z); bf16_t* OB = (bf16_t*)(ws + WS_KVR);
;     const int g = wave >> 2, w4 = wave & 3, r = lane & 31, hh = lane >> 5;
;     const int qr0 = qb * 128 + w4 * 32, nst = 2 * (qb + 1);
;     const size_t tokb = (size_t)b * SEQ;
;     bf16x8 qf[12];
;     { const bf16_t* qp = Q + (tokb + qr0 + r) * 768 + h * 192 + 8 * hh;
; #pragma unroll
;       for (int kk = 0; kk < 12; ++kk) qf[kk] = *(const bf16x8*)(qp + 16 * kk); }
;     f32x16 o[4];
; #pragma unroll
;     for (int i = 0; i < 4; ++i)
; #pragma unroll
;         for (int j = 0; j < 16; ++j) o[i][j] = 0.f;
;     float mrow = -INFINITY, lrow = 0.f;
;     const bf16_t* kbase = KB + tokb * 768 + h * 192;
;     const bf16_t* vbase = VT + (size_t)((b * 4 + h) * 128) * SEQ;
;     int krow[3], kcol[3];
; #pragma unroll
;     for (int e = 0; e < 3; ++e) { const int c = tid + 512 * e; krow[e] = c / 24; kcol[e] = c % 24; }
;     u32x4 pk[3], pv[2];
;     ...
;     AT_LOAD(0); AT_WRITE(0);
.LBB0_444:
	s_mov_b32 s3, s33
	s_mov_b64 s[0:1], s[50:51]
	s_barrier
	v_mbcnt_lo_u32_b32 v183, -1, 0
	v_mbcnt_hi_u32_b32 v183, -1, v183
	s_mov_b32 s0, 0x2aaaaaab
	v_lshl_add_u32 v14, s3, 6, v183
	v_mul_hi_i32 v0, v14, s0
	v_lshrrev_b32_e32 v2, 31, v0
	v_ashrrev_i32_e32 v0, 2, v0
	v_add_u32_e32 v40, v0, v2
	v_mul_lo_u32 v0, v40, 24
	v_add_u32_e32 v20, 0x200, v14
	v_sub_u32_e32 v41, v14, v0
	v_mul_hi_i32 v0, v20, s0
	v_lshrrev_b32_e32 v2, 31, v0
	v_ashrrev_i32_e32 v0, 2, v0
	v_add_u32_e32 v42, v0, v2
	v_mul_lo_u32 v0, v42, 24
	v_sub_u32_e32 v43, v20, v0
	v_add_u32_e32 v0, 0x400, v14
	v_mul_hi_i32 v2, v0, s0
	v_lshrrev_b32_e32 v3, 31, v2
	v_ashrrev_i32_e32 v2, 2, v2
	v_add_u32_e32 v44, v2, v3
	v_mul_lo_u32 v2, v44, 24
	v_sub_u32_e32 v45, v0, v2
	v_lshlrev_b32_e32 v4, 3, v41
	v_lshlrev_b32_e32 v6, 3, v43
	v_mov_b64_e32 v[10:11], s[52:53]
	v_ashrrev_i32_e32 v5, 31, v4
	v_ashrrev_i32_e32 v7, 31, v6
	v_lshlrev_b32_e32 v12, 3, v45
	v_mad_i64_i32 v[2:3], s[0:1], v40, s76, v[10:11]
	v_lshlrev_b64 v[22:23], 1, v[4:5]
	v_mad_i64_i32 v[4:5], s[0:1], v42, s76, v[10:11]
	v_lshlrev_b64 v[24:25], 1, v[6:7]
	v_ashrrev_i32_e32 v13, 31, v12
	v_lshlrev_b32_e32 v0, 4, v183
	v_ashrrev_i32_e32 v28, 3, v14
	v_lshl_add_u64 v[2:3], v[2:3], 0, v[22:23]
	v_lshl_add_u64 v[6:7], v[4:5], 0, v[24:25]
	v_mad_i64_i32 v[10:11], s[0:1], v44, s76, v[10:11]
	v_lshlrev_b64 v[26:27], 1, v[12:13]
	v_and_b32_e32 v0, 0x70, v0
	v_ashrrev_i32_e32 v29, 31, v28
	v_ashrrev_i32_e32 v32, 3, v20
	global_load_dwordx4 v[2:5], v[2:3], off
	s_nop 0
	global_load_dwordx4 v[6:9], v[6:7], off
	v_lshl_add_u64 v[10:11], v[10:11], 0, v[26:27]
	v_lshl_add_u64 v[18:19], s[74:75], 0, v[0:1]
	v_lshlrev_b64 v[30:31], 13, v[28:29]
	v_ashrrev_i32_e32 v33, 31, v32
	s_and_b32 s0, s72, 15
	s_and_b32 s20, s3, 3
	global_load_dwordx4 v[10:13], v[10:11], off
	v_lshl_add_u64 v[14:15], v[18:19], 0, v[30:31]
	v_lshlrev_b64 v[34:35], 13, v[32:33]
	s_lshl_b32 s4, s0, 7
	s_lshl_b32 s0, s94, 7
	s_lshl_b32 s5, s20, 5
	global_load_dwordx4 v[14:17], v[14:15], off
	v_lshl_add_u64 v[18:19], v[18:19], 0, v[34:35]
	v_and_b32_e32 v205, 31, v183
	s_or_b32 s36, s5, s0
	v_readlane_b32 s0, v254, 48
	global_load_dwordx4 v[18:21], v[18:19], off
	v_or_b32_e32 v33, s66, v205
	v_readlane_b32 s1, v254, 49
	v_or_b32_e32 v202, s36, v33
	v_ashrrev_i32_e32 v29, 5, v183
	v_mov_b64_e32 v[36:37], s[0:1]
	v_mad_u64_u32 v[36:37], s[0:1], v202, s76, v[36:37]
	s_lshl_b32 s0, s67, 1
	s_mov_b32 s1, s93
	v_lshlrev_b32_e32 v38, 3, v29
	v_lshl_add_u64 v[36:37], v[36:37], 0, s[0:1]
	v_ashrrev_i32_e32 v39, 31, v38
	v_lshl_add_u64 v[36:37], v[38:39], 1, v[36:37]
	s_nop 0
	s_nop 0
	v_readfirstlane_b32 s0, v36
	v_readfirstlane_b32 s1, v37
	s_lshr_b32 vcc_hi, s3, 2
	s_mul_i32 vcc_lo, s20, 0x3200
	s_add_u32 vcc_lo, vcc_lo, 0x15800
	s_mulk_i32 vcc_hi, 0x180
	v_add_u32_e32 v78, vcc_hi, v183
	v_mul_u32_u24_e32 v79, 0xaaab, v78
	v_lshrrev_b32_e32 v79, 20, v79
	v_mul_u32_u24_e32 v80, 24, v79
	v_sub_u32_e32 v80, v78, v80
	v_lshlrev_b32_e32 v80, 4, v80
	v_mad_u32_u24 v81, v79, s76, v80
	v_mad_u32_u24 v66, v79, s77, v80
	v_add_u32_e32 v66, vcc_lo, v66
	global_load_dwordx4 v[130:133], v81, s[0:1]
	v_add_u32_e32 v78, 64, v78
	v_mul_u32_u24_e32 v79, 0xaaab, v78
	v_lshrrev_b32_e32 v79, 20, v79
	v_mul_u32_u24_e32 v80, 24, v79
	v_sub_u32_e32 v80, v78, v80
	v_lshlrev_b32_e32 v80, 4, v80
	v_mad_u32_u24 v81, v79, s76, v80
	v_mad_u32_u24 v67, v79, s77, v80
	v_add_u32_e32 v67, vcc_lo, v67
	global_load_dwordx4 v[134:137], v81, s[0:1]
	v_add_u32_e32 v78, 64, v78
	v_mul_u32_u24_e32 v79, 0xaaab, v78
	v_lshrrev_b32_e32 v79, 20, v79
	v_mul_u32_u24_e32 v80, 24, v79
	v_sub_u32_e32 v80, v78, v80
	v_lshlrev_b32_e32 v80, 4, v80
	v_mad_u32_u24 v81, v79, s76, v80
	v_mad_u32_u24 v68, v79, s77, v80
	v_add_u32_e32 v68, vcc_lo, v68
	global_load_dwordx4 v[138:141], v81, s[0:1]
	v_add_u32_e32 v78, 64, v78
	v_mul_u32_u24_e32 v79, 0xaaab, v78
	v_lshrrev_b32_e32 v79, 20, v79
	v_mul_u32_u24_e32 v80, 24, v79
	v_sub_u32_e32 v80, v78, v80
	v_lshlrev_b32_e32 v80, 4, v80
	v_mad_u32_u24 v81, v79, s76, v80
	v_mad_u32_u24 v69, v79, s77, v80
	v_add_u32_e32 v69, vcc_lo, v69
	global_load_dwordx4 v[142:145], v81, s[0:1]
	v_add_u32_e32 v78, 64, v78
	v_mul_u32_u24_e32 v79, 0xaaab, v78
	v_lshrrev_b32_e32 v79, 20, v79
	v_mul_u32_u24_e32 v80, 24, v79
	v_sub_u32_e32 v80, v78, v80
	v_lshlrev_b32_e32 v80, 4, v80
	v_mad_u32_u24 v81, v79, s76, v80
	v_mad_u32_u24 v70, v79, s77, v80
	v_add_u32_e32 v70, vcc_lo, v70
	global_load_dwordx4 v[146:149], v81, s[0:1]
	v_add_u32_e32 v78, 64, v78
	v_mul_u32_u24_e32 v79, 0xaaab, v78
	v_lshrrev_b32_e32 v79, 20, v79
	v_mul_u32_u24_e32 v80, 24, v79
	v_sub_u32_e32 v80, v78, v80
	v_lshlrev_b32_e32 v80, 4, v80
	v_mad_u32_u24 v81, v79, s76, v80
	v_mad_u32_u24 v71, v79, s77, v80
	v_add_u32_e32 v71, vcc_lo, v71
	global_load_dwordx4 v[150:153], v81, s[0:1]
	v_mul_lo_u32 v207, v40, s77
	v_lshlrev_b32_e32 v208, 4, v41
	v_add3_u32 v33, 0, v207, v208
	v_mul_lo_u32 v209, v42, s77
	v_lshlrev_b32_e32 v210, 4, v43
	v_mul_lo_u32 v211, v44, s77
	v_lshlrev_b32_e32 v212, 4, v45
	s_movk_i32 s0, 0x90
	v_bfe_u32 v222, v0, 4, 1
	v_and_b32_e32 v213, 0x60, v0
	v_lshl_or_b32 v213, v222, 3, v213
	v_mul_lo_u32 v214, v28, s0
	s_ashr_i32 s21, s3, 2
	v_mul_lo_u32 v215, v32, s0
	s_lshl_b32 s53, s21, 5
	v_lshlrev_b32_e32 v182, 2, v29
	s_or_b32 s0, s4, s5
	v_or_b32_e32 v30, v30, v0
	v_or_b32_e32 v34, v34, v0
	s_or_b32 s52, s4, 64
	s_or_b32 s56, s36, 31
	v_mov_b32_e32 v0, v1
	v_mov_b32_e32 v203, 0
	v_mov_b32_e32 v204, 0xff800000
	s_waitcnt vmcnt(10)
	ds_write_b128 v33, v[2:5]
	v_add3_u32 v2, 0, v209, v210
	s_waitcnt vmcnt(9)
	ds_write_b128 v2, v[6:9]
	v_add3_u32 v2, 0, v211, v212
	v_lshlrev_b32_e32 v3, 4, v29
	v_mov_b32_e32 v6, v1
	v_mov_b32_e32 v7, v1
	v_mov_b32_e32 v8, v1
	s_waitcnt vmcnt(8)
; #define AT_LOAD(st) do { _Pragma("unroll") for (int e = 0; e < 3; ++e) pk[e] = *(const u32x4*)(kbase + (size_t)((st) * 64 + krow[e]) * 768 + kcol[e] * 8); \
;         _Pragma("unroll") for (int e = 0; e < 2; ++e) { const int c = tid + 512 * e; pv[e] = *(const u32x4*)(vbase + (size_t)(c >> 3) * SEQ + (st) * 64 + (c & 7) * 8); } } while (0)
; DI void attn_unit(const Params& p, int b, int h, int qb, LAS unsigned char* lds, int tid, int lane, int wave) {
;     ...
;     bf16x8 qf[12];
;     { const bf16_t* qp = Q + (tokb + qr0 + r) * 768 + h * 192 + 8 * hh;
; #pragma unroll
;       for (int kk = 0; kk < 12; ++kk) qf[kk] = *(const bf16x8*)(qp + 16 * kk); }
;     f32x16 o[4];
; #pragma unroll
;     for (int i = 0; i < 4; ++i)
; #pragma unroll
;         for (int j = 0; j < 16; ++j) o[i][j] = 0.f;
;     float mrow = -INFINITY, lrow = 0.f;
;     const bf16_t* kbase = KB + tokb * 768 + h * 192;
;     const bf16_t* vbase = VT + (size_t)((b * 4 + h) * 128) * SEQ;
;     int krow[3], kcol[3];
; #pragma unroll
;     for (int e = 0; e < 3; ++e) { const int c = tid + 512 * e; krow[e] = c / 24; kcol[e] = c % 24; }
;     u32x4 pk[3], pv[2];
;     ...
;     AT_LOAD(0); AT_WRITE(0);
;     __syncthreads();
	ds_write_b128 v2, v[10:13]
	v_add3_u32 v2, v213, v214, s65
	v_mov_b32_e32 v9, v1
	v_mov_b32_e32 v10, v1
	v_mov_b32_e32 v11, v1
	v_mov_b32_e32 v12, v1
	s_waitcnt vmcnt(7)
	ds_write2_b64 v2, v[14:15], v[16:17] offset1:2
	v_add3_u32 v2, v213, v215, s65
	v_mov_b32_e32 v14, v1
	v_mov_b32_e32 v15, v1
	v_mov_b32_e32 v13, v1
	s_waitcnt vmcnt(6)
	ds_write2_b64 v2, v[18:19], v[20:21] offset1:2
	v_or_b32_e32 v2, s53, v205
	v_mul_lo_u32 v2, v2, s77
	v_add3_u32 v216, 0, v2, v3
	v_mul_u32_u24_e32 v2, 0x90, v205
	v_lshlrev_b32_e32 v3, 2, v182
	v_lshl_add_u32 v3, s53, 1, v3
	v_add3_u32 v206, 0, v2, v3
	v_or_b32_e32 v2, s0, v205
	v_sub_u32_e32 v2, v2, v182
	v_subrev_u32_e32 v217, s53, v2
	v_lshl_add_u64 v[2:3], v[30:31], 0, s[92:93]
	s_mov_b64 s[0:1], 0xe600080
	v_lshl_add_u64 v[184:185], v[2:3], 0, s[0:1]
	v_lshl_add_u64 v[2:3], v[34:35], 0, s[92:93]
	v_lshl_add_u64 v[186:187], v[2:3], 0, s[0:1]
	s_mul_i32 s0, s2, 0x180
	s_add_u32 s0, s0, s54
	s_addc_u32 s1, 0, s55
	v_mov_b64_e32 v[2:3], s[0:1]
	v_mad_i64_i32 v[4:5], s[0:1], v44, s76, v[2:3]
	v_lshl_add_u64 v[188:189], v[4:5], 0, v[26:27]
	v_mad_i64_i32 v[4:5], s[0:1], v42, s76, v[2:3]
	v_mad_i64_i32 v[2:3], s[0:1], v40, s76, v[2:3]
	v_lshl_add_u64 v[190:191], v[4:5], 0, v[24:25]
	v_lshl_add_u64 v[192:193], v[2:3], 0, v[22:23]
	v_mov_b32_e32 v2, v1
	v_mov_b32_e32 v3, v1
	v_mov_b32_e32 v4, v1
	v_mov_b32_e32 v5, v1
	v_mov_b64_e32 v[64:65], v[14:15]
	v_mov_b64_e32 v[48:49], v[14:15]
	v_mov_b64_e32 v[32:33], v[14:15]
	v_mov_b64_e32 v[62:63], v[12:13]
	v_mov_b64_e32 v[60:61], v[10:11]
	v_mov_b64_e32 v[58:59], v[8:9]
	v_mov_b64_e32 v[56:57], v[6:7]
	v_mov_b64_e32 v[54:55], v[4:5]
	v_mov_b64_e32 v[52:53], v[2:3]
	v_mov_b64_e32 v[50:51], v[0:1]
	v_mov_b64_e32 v[46:47], v[12:13]
	v_mov_b64_e32 v[44:45], v[10:11]
	v_mov_b64_e32 v[42:43], v[8:9]
	v_mov_b64_e32 v[40:41], v[6:7]
	v_mov_b64_e32 v[38:39], v[4:5]
	v_mov_b64_e32 v[36:37], v[2:3]
	v_mov_b64_e32 v[34:35], v[0:1]
	v_mov_b64_e32 v[30:31], v[12:13]
	v_mov_b64_e32 v[28:29], v[10:11]
	v_mov_b64_e32 v[26:27], v[8:9]
	v_mov_b64_e32 v[24:25], v[6:7]
	v_mov_b64_e32 v[22:23], v[4:5]
	v_mov_b64_e32 v[20:21], v[2:3]
	v_mov_b64_e32 v[18:19], v[0:1]
	v_mov_b64_e32 v[16:17], v[14:15]
	s_mov_b32 s54, 0
	v_mov_b64_e32 v[14:15], v[12:13]
	v_mov_b64_e32 v[12:13], v[10:11]
	v_mov_b64_e32 v[10:11], v[8:9]
	v_mov_b64_e32 v[8:9], v[6:7]
	v_mov_b64_e32 v[6:7], v[4:5]
	v_mov_b64_e32 v[4:5], v[2:3]
	v_mov_b64_e32 v[2:3], v[0:1]
	s_mov_b32 s55, 0
	s_waitcnt vmcnt(5)
	ds_write_b128 v66, v[130:133]
	s_waitcnt vmcnt(4)
	ds_write_b128 v67, v[134:137]
	s_waitcnt vmcnt(3)
	ds_write_b128 v68, v[138:141]
	s_waitcnt vmcnt(2)
	ds_write_b128 v69, v[142:145]
	s_waitcnt vmcnt(1)
	ds_write_b128 v70, v[146:149]
	s_waitcnt vmcnt(0)
	ds_write_b128 v71, v[150:153]
	s_waitcnt lgkmcnt(0)
	s_barrier
	v_lshrrev_b32_e32 v78, 5, v183
	v_and_b32_e32 v79, 31, v183
	v_mul_u32_u24_e32 v79, s77, v79
	v_lshl_add_u32 v79, v78, 4, v79
	s_mul_i32 vcc_lo, s20, 0x3200
	s_add_u32 vcc_lo, vcc_lo, 0x15800
	v_add_u32_e32 v79, vcc_lo, v79
	ds_read_b128 v[126:129], v79
	ds_read_b128 v[122:125], v79 offset:32
	ds_read_b128 v[118:121], v79 offset:64
	ds_read_b128 v[114:117], v79 offset:96
	ds_read_b128 v[110:113], v79 offset:128
	ds_read_b128 v[106:109], v79 offset:160
	ds_read_b128 v[102:105], v79 offset:192
	ds_read_b128 v[98:101], v79 offset:224
	ds_read_b128 v[94:97], v79 offset:256
	ds_read_b128 v[90:93], v79 offset:288
	ds_read_b128 v[86:89], v79 offset:320
	ds_read_b128 v[82:85], v79 offset:352
	s_waitcnt vmcnt(0)
	v_mov_b64_e32 v[230:231], 0
	v_mov_b64_e32 v[232:233], 0
	v_mov_b64_e32 v[234:235], 0
	v_mov_b64_e32 v[236:237], 0
	v_mov_b64_e32 v[238:239], 0
	v_mov_b64_e32 v[240:241], 0
	v_mov_b64_e32 v[242:243], 0
	v_mov_b64_e32 v[244:245], 0
	v_mov_b32_e32 v246, 0xff800000
	v_lshl_add_u32 v222, s3, 6, v183
	v_and_b32_e32 v222, 0xff, v222
	s_movk_i32 s0, 0x600
	s_movk_i32 s1, 0x190
	s_cmp_lg_u32 s21, 0
	s_cbranch_scc1 .Lal2_b
	v_mov_b32_e32 v223, v222
	v_mul_u32_u24_e32 v224, 0xaaab, v223
	v_lshrrev_b32_e32 v224, 20, v224
	v_mul_u32_u24_e32 v225, 24, v224
	v_sub_u32_e32 v225, v223, v225
	v_lshlrev_b32_e32 v225, 4, v225
	v_mad_u32_u24 v184, v224, s0, v225
	v_mad_u32_u24 v190, v224, s1, v225
	v_add_u32_e32 v223, 256, v222
	v_mul_u32_u24_e32 v224, 0xaaab, v223
	v_lshrrev_b32_e32 v224, 20, v224
	v_mul_u32_u24_e32 v225, 24, v224
	v_sub_u32_e32 v225, v223, v225
	v_lshlrev_b32_e32 v225, 4, v225
	v_mad_u32_u24 v185, v224, s0, v225
	v_mad_u32_u24 v191, v224, s1, v225
	v_add_u32_e32 v223, 512, v222
	v_mul_u32_u24_e32 v224, 0xaaab, v223
	v_lshrrev_b32_e32 v224, 20, v224
	v_mul_u32_u24_e32 v225, 24, v224
	v_sub_u32_e32 v225, v223, v225
	v_lshlrev_b32_e32 v225, 4, v225
	v_mad_u32_u24 v186, v224, s0, v225
	v_mad_u32_u24 v192, v224, s1, v225
	v_add_u32_e32 v223, 768, v222
	v_mul_u32_u24_e32 v224, 0xaaab, v223
	v_lshrrev_b32_e32 v224, 20, v224
	v_mul_u32_u24_e32 v225, 24, v224
	v_sub_u32_e32 v225, v223, v225
	v_lshlrev_b32_e32 v225, 4, v225
	v_mad_u32_u24 v187, v224, s0, v225
	v_mad_u32_u24 v193, v224, s1, v225
	v_add_u32_e32 v223, 1024, v222
	v_mul_u32_u24_e32 v224, 0xaaab, v223
	v_lshrrev_b32_e32 v224, 20, v224
	v_mul_u32_u24_e32 v225, 24, v224
	v_sub_u32_e32 v225, v223, v225
	v_lshlrev_b32_e32 v225, 4, v225
	v_mad_u32_u24 v188, v224, s0, v225
	v_mad_u32_u24 v207, v224, s1, v225
	v_add_u32_e32 v223, 1280, v222
	v_mul_u32_u24_e32 v224, 0xaaab, v223
	v_lshrrev_b32_e32 v224, 20, v224
	v_mul_u32_u24_e32 v225, 24, v224
	v_sub_u32_e32 v225, v223, v225
	v_lshlrev_b32_e32 v225, 4, v225
	v_mad_u32_u24 v189, v224, s0, v225
	v_mad_u32_u24 v208, v224, s1, v225
	s_branch .Lal2_done
